# ph5 chain side: weight-transpose jobs wupg/wout/wf2 run on the workgroups idle in the partial GEMM rounds (before the two sub-barriers) instead of after the up-projection
# baseline (speedup 1.0000x reference)
; DI int GDIM() { return (int)__ockl_get_num_groups(0); }
; DI int BID() { int t = __builtin_amdgcn_workgroup_id_x(); asm volatile("" : "+s"(t)); return t; }
; DI unsigned xcc_id() { return (unsigned)__builtin_amdgcn_s_getreg((3 << 11) | 20) & 7u; }
; __global__ void __launch_bounds__(512, 2) hybrid_fwd(Params p_arg) {
;     ...
;     const unsigned my_xcc = xcc_id();
;     if (__builtin_amdgcn_workitem_id_x() == 0) __hip_atomic_fetch_add((unsigned*)(p_arg.ws + O_BAR) + 512 + 64 * my_xcc, 1u, __ATOMIC_RELAXED, __HIP_MEMORY_SCOPE_AGENT);
;     unsigned nx_mine = 0, nxcc_act = 0;
;     for (int st = 0; st < 24; ++st) {
;         const int l = st < 2 ? 0 : (st - 2) / 11;
;         const int ph = st < 2 ? st : 2 + (st - 2) % 11;
;         PP p = (PP)__builtin_amdgcn_kernarg_segment_ptr();
;         asm volatile("" : "+s"(p));
;         const int G = GDIM(), bid = BID();
;         unsigned char* ws = p->ws;
;         float* mod = (float*)(ws + O_MOD);
;         bf16_t* hbuf = (bf16_t*)(ws + O_D);
;         bf16_t* ybuf = (bf16_t*)(ws + O_B);
;         float* x1buf = (float*)(ws + O_C);
;         const float* ml = mod + l * 12288;
.LBB0_6:
	s_or_b64 exec, exec, s[0:1]
	s_waitcnt lgkmcnt(0)
	s_ashr_i32 s0, s85, 31
	v_writelane_b32 v254, s0, 6
	s_sub_i32 s0, s85, 32
	s_ashr_i32 s1, s0, 31
	v_writelane_b32 v254, s1, 7
	v_writelane_b32 v254, s0, 8
	s_mul_i32 s0, s0, 3
	v_writelane_b32 v254, s0, 9
	s_add_i32 s0, s85, 0xffffffa0
	s_sub_i32 s86, s85, 64
	s_lshl_b32 s62, s85, 4
	s_lshl_b32 s26, s85, 7
	v_writelane_b32 v254, s0, 10
	s_lshl_b32 s0, s0, 9
	s_add_i32 s1, s85, -8
	s_lshl_b32 s68, s86, 9
	s_cmp_eq_u32 s85, 0x7fffffff
	v_writelane_b32 v254, s1, 11
	s_cselect_b64 s[2:3], -1, 0
	v_writelane_b32 v254, s2, 12
	s_cmp_eq_u32 s8, 0
	v_lshrrev_b32_e32 v1, 20, v0
	v_writelane_b32 v254, s3, 13
	s_cselect_b64 s[2:3], -1, 0
	v_writelane_b32 v254, s2, 14
	s_cmp_eq_u32 s8, 1
	v_lshrrev_b32_e32 v0, 10, v0
	v_writelane_b32 v254, s3, 15
	s_cselect_b64 s[2:3], -1, 0
	v_writelane_b32 v254, s2, 16
	s_cmp_eq_u32 s8, 2
	v_or_b32_e32 v0, v0, v1
	v_writelane_b32 v254, s3, 17
	s_cselect_b64 s[2:3], -1, 0
	v_writelane_b32 v254, s2, 18
	s_cmp_eq_u32 s8, 3
	s_movk_i32 s1, 0x3ff
	v_writelane_b32 v254, s3, 19
	s_cselect_b64 s[2:3], -1, 0
	v_writelane_b32 v254, s2, 20
	s_cmp_eq_u32 s8, 4
	v_and_or_b32 v0, v0, s1, v201
	v_writelane_b32 v254, s3, 21
	s_cselect_b64 s[2:3], -1, 0
	v_writelane_b32 v254, s2, 22
	s_cmp_eq_u32 s8, 5
	v_mov_b32_e32 v3, 0
	v_writelane_b32 v254, s3, 23
	s_cselect_b64 s[2:3], -1, 0
	v_writelane_b32 v254, s2, 24
	s_cmp_eq_u32 s8, 6
	v_mbcnt_lo_u32_b32 v1, -1, 0
	v_writelane_b32 v254, s3, 25
	s_cselect_b64 s[2:3], -1, 0
	v_writelane_b32 v254, s2, 26
	s_cmp_eq_u32 s8, 7
	s_movk_i32 s65, 0x3000
	v_writelane_b32 v254, s3, 27
	s_cselect_b64 s[2:3], -1, 0
	v_writelane_b32 v254, s2, 28
	s_ashr_i32 s1, s0, 31
	s_ashr_i32 s69, s68, 31
	v_writelane_b32 v254, s3, 29
	s_add_i32 s2, 0, 0x4200
	v_writelane_b32 v254, s2, 30
	v_cmp_eq_u32_e64 s[2:3], 0, v0
	s_lshl_b64 s[30:31], s[68:69], 4
	s_ashr_i32 s63, s62, 31
	v_writelane_b32 v254, s2, 31
	s_lshl_b32 s27, s85, 14
	s_lshl_b64 s[28:29], s[62:63], 12
	v_writelane_b32 v254, s3, 32
	s_mov_b32 s2, s0
	v_writelane_b32 v254, s2, 33
	s_lshl_b64 s[0:1], s[0:1], 4
	s_movk_i32 s74, 0x1ff
	v_writelane_b32 v254, s3, 34
	v_writelane_b32 v254, s0, 35
	s_movk_i32 s6, 0x80
	s_movk_i32 s8, 0x1000
	v_writelane_b32 v254, s1, 36
	v_writelane_b32 v254, s85, 37
	v_writelane_b32 v254, s64, 38
	v_writelane_b32 v254, s26, 39
	v_writelane_b32 v254, s68, 40
	s_mov_b32 s10, 0x800000
	s_movk_i32 s12, 0x500
	v_writelane_b32 v254, s69, 41
	v_writelane_b32 v254, s27, 42
	v_writelane_b32 v254, s28, 43
	s_mov_b32 s13, 0x3fb8aa3b
	v_mov_b32_e32 v218, 0x3c0881c4
	v_writelane_b32 v254, s29, 44
	v_mov_b32_e32 v219, 0xbab64f3b
	v_mbcnt_hi_u32_b32 v220, -1, v1
	v_mov_b32_e32 v221, 1
	v_mov_b32_e32 v222, 0x2da22000
	v_mov_b64_e32 v[194:195], 0x200
	v_mov_b64_e32 v[196:197], 0x1ff
	v_mov_b32_e32 v223, 0x7f800000
	v_not_b32_e32 v224, 63
	v_not_b32_e32 v225, 31
	v_mov_b32_e32 v226, 0x7fc00000
	v_mov_b32_e32 v240, v3
	v_mov_b32_e32 v241, v3
	v_mov_b32_e32 v242, v3
	v_mov_b32_e32 v243, v3
	v_mov_b32_e32 v227, 0x1f8
	v_mov_b64_e32 v[198:199], 0x900
	v_mov_b32_e32 v200, 0x3727c5ac
	v_mov_b32_e32 v229, 0
	v_mov_b32_e32 v228, 0
	s_movk_i32 s14, 0x7c0
	s_mov_b32 s15, 0xc2ce8ed0
	s_mov_b32 s16, 0x42b17218
	s_brev_b32 s17, 18
	s_mov_b32 s18, 0xfe5163ab
	s_mov_b32 s19, 0x3c439041
	s_mov_b32 s76, 0xdb629599
	s_mov_b32 s77, 0xf534ddc0
	s_mov_b32 s66, 0xfc2757d1
	s_mov_b32 s67, 0x4e441529
	s_mov_b32 s7, 0xa2f9836e
	s_mov_b32 s87, 0x3fc90fda
	s_mov_b32 s75, 0x3f22f983
	s_mov_b32 s80, 0xbfc90fda
	s_brev_b32 s81, 1
	s_movk_i32 s11, 0x1f8
	s_movk_i32 s91, 0x63f
	s_add_i32 s33, 0, 0x6200
	s_movk_i32 s9, 0x1dff
	s_mov_b32 s96, 0x66666667
	s_movk_i32 s97, 0xffb0
	s_movk_i32 s90, 0xfd80
	s_mov_b32 s89, 0x9dff
	s_movk_i32 s70, 0x3dff
	s_mov_b32 s71, 0
	s_lshl_b64 s[72:73], s[62:63], 13
	s_mov_b64 s[78:79], 0x80
	s_mov_b32 s88, 0x3fb504f3
	s_mov_b32 s57, 0
	v_writelane_b32 v254, s30, 45
	s_nop 1
	v_writelane_b32 v254, s31, 46
	s_mov_b32 s0, 0
	v_writelane_b32 v254, s0, 60
	s_branch .LBB0_10

; __global__ void __launch_bounds__(512, 2) hybrid_fwd(Params p_arg) {
;     ...
;                 { Gemm g{(const bf16_t*)(ws + O_E), (const bf16_t*)(ws + O_BT2), 640, 640, 640}; OrderS5Y S{G2, c2};
;                   EpiS5Y E{(const bf16_t*)(ws + O_E), p->in[12] + l * 1024, (bf16_t*)(ws + O_ZS)}; gemm_phase(lds, g, S, E); }
;                 subbar(sb, (unsigned)((3 * l + 1) * G2));
;                 { Gemm g{(const bf16_t*)(ws + O_ZS), (const bf16_t*)(ws + O_WGLU), 1024, 1024, 1024}; StaticOrder S; S.init(L, 1024, G2, c2);
;                   EpiGlu E{(const bf16_t*)(ws + O_ZS), p->in[14] + l * 1024, (bf16_t*)(ws + O_Y2)}; gemm_phase(lds, g, S, E); }
;                 subbar(sb, (unsigned)((3 * l + 2) * G2));
;                 { Gemm g{(const bf16_t*)(ws + O_Y2), (const bf16_t*)(ws + O_WUPS), 1024, 1024, 1024}; StaticOrder S; S.init(L, 2048, G2, c2);
;                   EpiUp<0> E{(const bf16_t*)(ws + O_SGS), nullptr, (bf16_t*)(ws + O_T1)}; gemm_phase(lds, g, S, E); }
;                 __syncthreads();
;                 phase_weights_b(lds, p, l, c2, G2);
.LBB0_120:
	s_cmp_lt_u32 s44, 32
	s_cbranch_scc1 .Lwb_skip1
	v_writelane_b32 v255, s2, 0
	v_writelane_b32 v255, s3, 1
	v_writelane_b32 v255, s20, 2
	v_writelane_b32 v255, s21, 3
	v_writelane_b32 v255, s22, 4
	v_writelane_b32 v255, s23, 5
	v_writelane_b32 v255, s26, 6
	v_writelane_b32 v255, s27, 7
	v_writelane_b32 v255, s28, 8
	v_writelane_b32 v255, s29, 9
	v_writelane_b32 v255, s30, 10
	v_writelane_b32 v255, s31, 11
	v_writelane_b32 v255, s34, 12
	s_sub_i32 s44, s44, 32
	s_sub_i32 s85, s85, 32
	s_sub_i32 s2, s85, 32
	v_writelane_b32 v254, s2, 8
	s_mov_b32 s2, 1
	v_writelane_b32 v254, s2, 60
	s_mov_b64 s[2:3], -1
	s_branch .LBB0_164
.Lwb_ret1:
	s_add_i32 s44, s44, 32
	s_add_i32 s85, s85, 32
	s_sub_i32 s2, s85, 32
	v_writelane_b32 v254, s2, 8
	s_mov_b32 s2, 0
	v_writelane_b32 v254, s2, 60
	v_readlane_b32 s2, v255, 0
	v_readlane_b32 s3, v255, 1
	v_readlane_b32 s20, v255, 2
	v_readlane_b32 s21, v255, 3
	v_readlane_b32 s22, v255, 4
	v_readlane_b32 s23, v255, 5
	v_readlane_b32 s26, v255, 6
	v_readlane_b32 s27, v255, 7
	v_readlane_b32 s28, v255, 8
	v_readlane_b32 s29, v255, 9
	v_readlane_b32 s30, v255, 10
	v_readlane_b32 s31, v255, 11
	v_readlane_b32 s34, v255, 12

; __global__ void __launch_bounds__(512, 2) hybrid_fwd(Params p_arg) {
;     ...
;                 { Gemm g{(const bf16_t*)(ws + O_ZS), (const bf16_t*)(ws + O_WGLU), 1024, 1024, 1024}; StaticOrder S; S.init(L, 1024, G2, c2);
;                   EpiGlu E{(const bf16_t*)(ws + O_ZS), p->in[14] + l * 1024, (bf16_t*)(ws + O_Y2)}; gemm_phase(lds, g, S, E); }
;                 subbar(sb, (unsigned)((3 * l + 2) * G2));
.LBB0_142:
	s_cmp_lt_u32 s44, 32
	s_cbranch_scc1 .Lwb_skip2
	v_writelane_b32 v255, s2, 0
	v_writelane_b32 v255, s3, 1
	v_writelane_b32 v255, s20, 2
	v_writelane_b32 v255, s21, 3
	v_writelane_b32 v255, s22, 4
	v_writelane_b32 v255, s23, 5
	v_writelane_b32 v255, s26, 6
	v_writelane_b32 v255, s27, 7
	v_writelane_b32 v255, s28, 8
	v_writelane_b32 v255, s29, 9
	v_writelane_b32 v255, s30, 10
	v_writelane_b32 v255, s31, 11
	v_writelane_b32 v255, s34, 12
	s_sub_i32 s44, s44, 32
	s_sub_i32 s85, s85, 32
	s_sub_i32 s2, s85, 32
	v_writelane_b32 v254, s2, 8
	s_mov_b32 s2, 2
	v_writelane_b32 v254, s2, 60
	s_branch .LBB0_213

; #define LAS __attribute__((address_space(3)))
; DI int TID() { int t = __builtin_amdgcn_workitem_id_x(); asm volatile("" : "+v"(t)); return t; }
; template <int MODE> DI void transpose_job(LAS unsigned char* lds, const float* src, int K, int N, bf16_t* dst, int bid, int nblk) {
;     const int tid = TID(), tn = (N + 63) >> 6, tk = K >> 6, ntile = tn * tk;
;     for (int t0 = bid; t0 < ntile; t0 += 2 * nblk) {
; #pragma unroll
;         for (int q = 0; q < 2; ++q) { const int t = t0 + q * nblk; LAS float* tl = (LAS float*)(lds + q * 16640);
;             if (t < ntile) { const int k0 = (t / tn) * 64, n0 = (t % tn) * 64;
; #pragma unroll
;                 for (int i = 0; i < 2; ++i) { const int kk = (tid >> 4) + 32 * i, nn = (tid & 15) * 4;
; __global__ void __launch_bounds__(512, 2) hybrid_fwd(Params p_arg) {
;     ...
;                 __syncthreads();
;                 phase_weights_b(lds, p, l, c2, G2);
.LBB0_164:
	s_waitcnt vmcnt(0)
	v_mov_b32_e32 v4, v201
	s_andn2_b64 vcc, exec, s[2:3]
	s_waitcnt lgkmcnt(0)
	s_barrier
	v_readlane_b32 s20, v254, 60
	s_cmp_eq_u32 s20, 0
	s_cbranch_scc1 .LBB0_194
	s_cbranch_vccnz .LBB0_179
	s_load_dwordx2 s[20:21], s[0:1], 0xa0
	s_add_u32 s2, s94, 0x2b00000
	v_readlane_b32 s22, v254, 49
	s_addc_u32 s3, s95, 0
	v_readlane_b32 s23, v254, 50
	s_and_b64 s[22:23], s[22:23], exec
	s_cselect_b32 s22, 0, 0x800000
	v_lshlrev_b32_e32 v0, 2, v4
	s_waitcnt lgkmcnt(0)
	s_add_u32 s20, s20, s22
	v_and_b32_e32 v14, 60, v0
	s_addc_u32 s21, s21, 0
	v_lshlrev_b32_e32 v2, 2, v14
	v_ashrrev_i32_e32 v13, 4, v4
	v_add_u32_e32 v5, 0, v2
	v_lshl_add_u64 v[0:1], s[20:21], 0, v[2:3]
	v_lshlrev_b32_e32 v2, 3, v4
	s_movk_i32 s20, 0x104
	v_ashrrev_i32_e32 v15, 3, v4
	v_and_b32_e32 v12, 56, v2
	v_mul_lo_u32 v2, v13, s20
	v_lshl_add_u32 v16, v15, 2, 0
	v_add_u32_e32 v17, 32, v13
	v_mul_u32_u24_e32 v18, 0x104, v12
	v_add_u32_e32 v19, v5, v2
	s_mov_b32 s30, s44
	s_branch .LBB0_168

; #define LAS __attribute__((address_space(3)))
; DI int TID() { int t = __builtin_amdgcn_workitem_id_x(); asm volatile("" : "+v"(t)); return t; }
; template <int MODE> DI void transpose_job(LAS unsigned char* lds, const float* src, int K, int N, bf16_t* dst, int bid, int nblk) {
;     const int tid = TID(), tn = (N + 63) >> 6, tk = K >> 6, ntile = tn * tk;
;     for (int t0 = bid; t0 < ntile; t0 += 2 * nblk) {
; #pragma unroll
;         for (int q = 0; q < 2; ++q) { const int t = t0 + q * nblk; LAS float* tl = (LAS float*)(lds + q * 16640);
;             if (t < ntile) { const int k0 = (t / tn) * 64, n0 = (t % tn) * 64;
; #pragma unroll
;                 for (int i = 0; i < 2; ++i) { const int kk = (tid >> 4) + 32 * i, nn = (tid & 15) * 4;
; DI void phase_weights_b(LAS unsigned char* lds, PP p, int l, int bid, int nblk) {
;     ...
;     transpose_job<0>(lds, p->in[21] + (size_t)l * 2048 * 2048, 2048, 2048, (bf16_t*)(ws + O_WOUT), bid, nblk);
;     transpose_job<2>(lds, p->in[24] + (size_t)l * 2048 * 11264, 2048, 11264, (bf16_t*)(ws + O_WF1), bid, nblk);
.LBB0_194:
	v_readlane_b32 s2, v254, 60
	s_cmp_eq_u32 s2, 1
	s_cbranch_scc1 .Lwb_ret1
	v_mov_b32_e32 v4, v201
	s_cmpk_gt_u32 s44, 0x15ff
	s_cbranch_scc1 .LBB0_213
	s_load_dwordx2 s[20:21], s[0:1], 0xc0
	s_add_u32 s2, s94, 0x3700000
	v_readlane_b32 s22, v254, 49
	s_addc_u32 s3, s95, 0
	v_readlane_b32 s23, v254, 50
	s_and_b64 s[22:23], s[22:23], exec
	s_cselect_b32 s22, 0, 0x5800000
	s_waitcnt lgkmcnt(0)
	s_add_u32 s20, s20, s22
	v_lshlrev_b32_e32 v0, 4, v4
	s_addc_u32 s21, s21, 0
	v_and_b32_e32 v2, 0xf0, v0
	v_ashrrev_i32_e32 v5, 4, v4
	v_lshl_add_u64 v[0:1], s[20:21], 0, v[2:3]
	v_ashrrev_i32_e32 v16, 3, v4
	v_lshlrev_b32_e32 v4, 3, v4
	s_movk_i32 s20, 0x104
	v_add_u32_e32 v2, 0, v2
	v_and_b32_e32 v4, 56, v4
	v_mul_lo_u32 v6, v5, s20
	v_lshl_add_u32 v17, v16, 2, 0
	v_add_u32_e32 v18, 32, v5
	v_mul_u32_u24_e32 v19, 0x104, v4
	v_add_u32_e32 v20, v2, v6
	s_mov_b32 s30, s44
	s_branch .LBB0_199

; #define LAS __attribute__((address_space(3)))
; DI int TID() { int t = __builtin_amdgcn_workitem_id_x(); asm volatile("" : "+v"(t)); return t; }
; template <int MODE> DI void transpose_job(LAS unsigned char* lds, const float* src, int K, int N, bf16_t* dst, int bid, int nblk) {
;     const int tid = TID(), tn = (N + 63) >> 6, tk = K >> 6, ntile = tn * tk;
;     for (int t0 = bid; t0 < ntile; t0 += 2 * nblk) {
; #pragma unroll
;         for (int q = 0; q < 2; ++q) { const int t = t0 + q * nblk; LAS float* tl = (LAS float*)(lds + q * 16640);
;             if (t < ntile) { const int k0 = (t / tn) * 64, n0 = (t % tn) * 64;
; #pragma unroll
;                 for (int i = 0; i < 2; ++i) { const int kk = (tid >> 4) + 32 * i, nn = (tid & 15) * 4;
; DI void phase_weights_b(LAS unsigned char* lds, PP p, int l, int bid, int nblk) {
;     ...
;     transpose_job<0>(lds, p->in[25] + (size_t)l * 5632 * 2048, 5632, 2048, (bf16_t*)(ws + O_WF2), bid, nblk);
.LBB0_213:
	v_readlane_b32 s2, v254, 60
	s_cmp_lg_u32 s2, 2
	s_cbranch_scc1 .LBB0_228
	v_mov_b32_e32 v4, v201
	s_cmpk_gt_u32 s44, 0xaff
	s_cbranch_scc1 .LBB0_228
	s_load_dwordx2 s[20:21], s[0:1], 0xc8
	s_add_u32 s2, s94, 0x6300000
	v_readlane_b32 s22, v254, 49
	s_addc_u32 s3, s95, 0
	v_readlane_b32 s23, v254, 50
	s_and_b64 s[22:23], s[22:23], exec
	s_cselect_b32 s22, 0, 0x2c00000
	v_lshlrev_b32_e32 v0, 2, v4
	s_waitcnt lgkmcnt(0)
	s_add_u32 s20, s20, s22
	v_and_b32_e32 v14, 60, v0
	s_addc_u32 s21, s21, 0
	v_lshlrev_b32_e32 v2, 2, v14
	v_ashrrev_i32_e32 v13, 4, v4
	v_add_u32_e32 v5, 0, v2
	v_lshl_add_u64 v[0:1], s[20:21], 0, v[2:3]
	v_lshlrev_b32_e32 v2, 3, v4
	s_movk_i32 s20, 0x104
	v_ashrrev_i32_e32 v15, 3, v4
	v_and_b32_e32 v12, 56, v2
	v_mul_lo_u32 v2, v13, s20
	v_lshl_add_u32 v16, v15, 2, 0
	v_add_u32_e32 v17, 32, v13
	v_mul_u32_u24_e32 v18, 0x104, v12
	v_add_u32_e32 v19, v5, v2
	s_mov_b32 s30, s44
	s_branch .LBB0_217

; DI void subbar(unsigned* cnt, unsigned target) {
;     asm volatile("s_waitcnt vmcnt(0) lgkmcnt(0)" ::: "memory");
;     __builtin_amdgcn_s_barrier();
;     if (__builtin_amdgcn_workitem_id_x() == 0) {
;         __builtin_amdgcn_fence(__ATOMIC_RELEASE, "agent");
;         asm volatile("s_waitcnt vmcnt(0) lgkmcnt(0)" ::: "memory");
;         __hip_atomic_fetch_add(cnt, 1u, __ATOMIC_RELAXED, __HIP_MEMORY_SCOPE_AGENT);
; __global__ void __launch_bounds__(512, 2) hybrid_fwd(Params p_arg) {
;     ...
;                 if (l == 0) {
;                     subbar(sb, (unsigned)(3 * G2));
;                     if (c2 < G2 - 64) phase_weights_a(lds, p, 1, c2, G2 - 64); else phase_s5pre(lds, p, 1, c2 - (G2 - 64), 64);
.LBB0_228:
	v_readlane_b32 s2, v254, 60
	s_cmp_eq_u32 s2, 2
	s_cbranch_scc1 .Lwb_ret2
	v_readlane_b32 s2, v254, 49
	v_readlane_b32 s3, v254, 50
	s_andn2_b64 vcc, exec, s[2:3]
	s_cbranch_vccnz .LBB0_351
	s_waitcnt vmcnt(0) lgkmcnt(0)
	s_barrier
	s_mov_b64 s[2:3], exec
	v_readlane_b32 s20, v254, 4
	v_readlane_b32 s21, v254, 5
	s_and_b64 s[20:21], s[2:3], s[20:21]
	s_mov_b64 exec, s[20:21]
	s_cbranch_execz .LBB0_235
	s_mov_b64 s[20:21], exec
	buffer_wbl2 sc1
	s_waitcnt vmcnt(0) lgkmcnt(0)
	s_waitcnt vmcnt(0) lgkmcnt(0)
	v_mbcnt_lo_u32_b32 v0, s20, 0
	v_mbcnt_hi_u32_b32 v0, s21, v0
	v_cmp_eq_u32_e32 vcc, 0, v0
	s_and_saveexec_b64 s[22:23], vcc
	s_cbranch_execz .LBB0_232
	s_bcnt1_i32_b64 s20, s[20:21]
	v_mov_b32_e32 v0, s20
	global_atomic_add v3, v0, s[24:25]

; __global__ void __launch_bounds__(512, 2) hybrid_fwd(Params p_arg) {
	.amdhsa_kernel _Z10hybrid_fwd6Params
		.amdhsa_group_segment_fixed_size 0
		.amdhsa_private_segment_fixed_size 0
		.amdhsa_kernarg_size 496
		.amdhsa_user_sgpr_count 2
		.amdhsa_user_sgpr_dispatch_ptr 0
		.amdhsa_user_sgpr_queue_ptr 0
		.amdhsa_user_sgpr_kernarg_segment_ptr 1
		.amdhsa_user_sgpr_dispatch_id 0
		.amdhsa_user_sgpr_kernarg_preload_length 0
		.amdhsa_user_sgpr_kernarg_preload_offset 0
		.amdhsa_user_sgpr_private_segment_size 0
		.amdhsa_uses_dynamic_stack 0
		.amdhsa_enable_private_segment 0
		.amdhsa_system_sgpr_workgroup_id_x 1
		.amdhsa_system_sgpr_workgroup_id_y 0
		.amdhsa_system_sgpr_workgroup_id_z 0
		.amdhsa_system_sgpr_workgroup_info 0
		.amdhsa_system_vgpr_workitem_id 2
		.amdhsa_next_free_vgpr 256
		.amdhsa_next_free_sgpr 100
		.amdhsa_accum_offset 256
		.amdhsa_reserve_vcc 1
		.amdhsa_float_round_mode_32 0
		.amdhsa_float_round_mode_16_64 0
		.amdhsa_float_denorm_mode_32 3
		.amdhsa_float_denorm_mode_16_64 3
		.amdhsa_dx10_clamp 1
		.amdhsa_ieee_mode 1
		.amdhsa_fp16_overflow 0
		.amdhsa_tg_split 0
		.amdhsa_exception_fp_ieee_invalid_op 0
		.amdhsa_exception_fp_denorm_src 0
		.amdhsa_exception_fp_ieee_div_zero 0
		.amdhsa_exception_fp_ieee_overflow 0
		.amdhsa_exception_fp_ieee_underflow 0
		.amdhsa_exception_fp_ieee_inexact 0
		.amdhsa_exception_int_div_zero 0
	.end_amdhsa_kernel

; __global__ void __launch_bounds__(512, 2) hybrid_fwd(Params p_arg) {
amdhsa.kernels:
  - .agpr_count:     0
    .args:
      - .offset:         0
        .size:           240
        .value_kind:     by_value
      - .offset:         240
        .size:           4
        .value_kind:     hidden_block_count_x
      - .offset:         244
        .size:           4
        .value_kind:     hidden_block_count_y
      - .offset:         248
        .size:           4
        .value_kind:     hidden_block_count_z
      - .offset:         252
        .size:           2
        .value_kind:     hidden_group_size_x
      - .offset:         254
        .size:           2
        .value_kind:     hidden_group_size_y
      - .offset:         256
        .size:           2
        .value_kind:     hidden_group_size_z
      - .offset:         258
        .size:           2
        .value_kind:     hidden_remainder_x
      - .offset:         260
        .size:           2
        .value_kind:     hidden_remainder_y
      - .offset:         262
        .size:           2
        .value_kind:     hidden_remainder_z
      - .offset:         280
        .size:           8
        .value_kind:     hidden_global_offset_x
      - .offset:         288
        .size:           8
        .value_kind:     hidden_global_offset_y
      - .offset:         296
        .size:           8
        .value_kind:     hidden_global_offset_z
      - .offset:         304
        .size:           2
        .value_kind:     hidden_grid_dims
      - .offset:         328
        .size:           8
        .value_kind:     hidden_multigrid_sync_arg
      - .offset:         360
        .size:           4
        .value_kind:     hidden_dynamic_lds_size
    .group_segment_fixed_size: 0
    .kernarg_segment_align: 8
    .kernarg_segment_size: 496
    .language:       OpenCL C
    .language_version:
      - 2
      - 0
    .max_flat_workgroup_size: 512
    .name:           _Z10hybrid_fwd6Params
    .private_segment_fixed_size: 0
    .sgpr_count:     106
    .sgpr_spill_count: 75
    .symbol:         _Z10hybrid_fwd6Params.kd
    .uniform_work_group_size: 1
    .uses_dynamic_stack: false
    .vgpr_count:     256
    .vgpr_spill_count: 0
    .wavefront_size: 64
